# attnB: static priority raise applied to waves 4-7 only (scalar branch around s_setprio)
# speedup vs baseline: 1.0040x; 1.0040x over previous
; #define LAS __attribute__((address_space(3)))
; __device__ __forceinline__ void attnB_unit(LAS unsigned char* lds, const unsigned char* ws, int unit, float lam, const float* subln_g) {
;     const int tid = threadIdx.x, lane = tid & 63, wid = __builtin_amdgcn_readfirstlane(tid >> 6), w = wid & 3, c = wid >> 2, r = lane & 31, h = lane >> 5;
;     const int qb = unit & 31, hd = (unit >> 5) & 3, b = unit >> 7, q0 = qb * 128;
;     const bf16* QB = (const bf16*)(ws + WS_QB); const bf16* KB = (const bf16*)(ws + WS_KB); const bf16* VB = (const bf16*)(ws + WS_VB); bf16* OB = (bf16*)(ws + WS_ATTA);
;     const size_t rowb = (size_t)b * SEQ;
;     const size_t qrow = rowb + q0 + 32 * w + r;
;     bf16x8 qf[4];
; #pragma unroll
;     for (int ks = 0; ks < 4; ++ks) qf[ks] = *(const bf16x8*)(QB + qrow * 512 + hd * 128 + c * 64 + 16 * ks + 8 * h);
;     const int rot = (qb * 2) & 63;
;     const bf16* kg = KB + (rowb + lane) * 512 + hd * 128 + wid * 8;
;     const bf16* vg0 = VB + (rowb + (wid & 3) * 16 + (lane >> 2)) * 512 + hd * 128 + (wid >> 2) * 32 + (lane & 3) * 8;
;     const unsigned ldsb = (unsigned)(unsigned long)lds;
;     const unsigned kd = ldsb + wid * BK_CH, vd0 = ldsb + 2 * BK_IMG + (wid >> 2) * BV_DB + (wid & 3) * 1024;
;     ...
;     const int i16 = lane & 15, qd = i16 >> 2, pp = i16 & 3, blk = (lane >> 4) & 1;
;     const int voff = 2 * BK_IMG + (4 * h + qd) * 64 + blk * 32 + pp * 8, koff = c * BK_IMG + h * BK_CH + r * 16;
; __global__ void __launch_bounds__(512, 2) fwd_kernel(Args A) {
;     ...
;         float d1 = 0.f, d2 = 0.f;
;         for (int i = 0; i < 64; ++i) { d1 += A.lq1[i] * A.lk1[i]; d2 += A.lq2[i] * A.lk2[i]; }
;         const float lam = expf(d1) - expf(d2) + 0.2f;
;         if (tid >= 256) __builtin_amdgcn_s_setprio(1);
.LBB0_288:
	s_waitcnt lgkmcnt(0)
	s_add_u32 s4, s70, s0
	s_addc_u32 s5, s71, s1
	global_load_dwordx4 v[4:7], v2, s[4:5]
	global_load_dwordx4 v[8:11], v2, s[4:5] offset:16
	s_add_u32 s4, s72, s0
	s_addc_u32 s5, s73, s1
	global_load_dwordx4 v[12:15], v2, s[4:5]
	global_load_dwordx4 v[16:19], v2, s[4:5] offset:16
	s_add_u32 s4, s74, s0
	s_addc_u32 s5, s75, s1
	global_load_dwordx4 v[20:23], v2, s[4:5]
	global_load_dwordx4 v[24:27], v2, s[4:5] offset:16
	s_add_u32 s4, s44, s0
	s_addc_u32 s5, s45, s1
	global_load_dwordx4 v[28:31], v2, s[4:5]
	global_load_dwordx4 v[32:35], v2, s[4:5] offset:16
	s_add_u32 s0, s0, 32
	s_addc_u32 s1, s1, 0
	s_cmpk_eq_i32 s0, 0x100
	s_waitcnt vmcnt(0)
	v_mov_b32_e32 v36, v4
	v_mov_b32_e32 v4, v6
	v_mov_b32_e32 v6, v8
	v_mov_b32_e32 v8, v10
	v_mov_b32_e32 v10, v12
	v_mov_b32_e32 v12, v14
	v_mov_b32_e32 v37, v20
	v_mov_b32_e32 v20, v5
	v_mov_b32_e32 v5, v22
	v_mov_b32_e32 v22, v7
	v_mov_b32_e32 v7, v24
	v_mov_b32_e32 v24, v9
	v_mov_b32_e32 v9, v26
	v_mov_b32_e32 v26, v11
	v_mov_b32_e32 v11, v28
	v_mov_b32_e32 v28, v13
	v_pk_fma_f32 v[0:1], v[36:37], v[10:11], v[0:1]
	v_mov_b32_e32 v13, v30
	v_pk_fma_f32 v[0:1], v[20:21], v[28:29], v[0:1]
	v_mov_b32_e32 v30, v15
	v_pk_fma_f32 v[0:1], v[4:5], v[12:13], v[0:1]
	v_mov_b32_e32 v14, v16
	v_mov_b32_e32 v15, v32
	v_pk_fma_f32 v[0:1], v[22:23], v[30:31], v[0:1]
	v_mov_b32_e32 v32, v17
	v_pk_fma_f32 v[0:1], v[6:7], v[14:15], v[0:1]
	v_mov_b32_e32 v16, v18
	v_mov_b32_e32 v17, v34
	v_pk_fma_f32 v[0:1], v[24:25], v[32:33], v[0:1]
	v_mov_b32_e32 v34, v19
	v_pk_fma_f32 v[0:1], v[8:9], v[16:17], v[0:1]
	s_nop 0
	v_pk_fma_f32 v[0:1], v[26:27], v[34:35], v[0:1]
	s_cbranch_scc0 .LBB0_288
	s_movk_i32 s0, 0xff
	v_cmp_lt_u32_e32 vcc, s0, v160
	s_and_saveexec_b64 s[0:1], vcc
	s_cbranch_execz .Lb_noprio
	s_setprio 1
.Lb_noprio:
	s_or_b64 exec, exec, s[0:1]
	s_cmpk_gt_i32 s78, 0x7ff
	s_cbranch_scc1 .LBB0_310
	v_mul_f32_e32 v2, 0x3fb8aa3b, v0
	s_mov_b32 s0, 0x3fb8aa3b
	v_rndne_f32_e32 v3, v2
	v_sub_f32_e32 v4, v2, v3
	v_fma_f32 v2, v0, s0, -v2
	v_fmac_f32_e32 v2, 0x32a5705f, v0
	v_add_f32_e32 v2, v4, v2
	v_exp_f32_e32 v2, v2
	v_cvt_i32_f32_e32 v3, v3
	s_mov_b32 s1, 0xc2ce8ed0
	v_cmp_ngt_f32_e32 vcc, s1, v0
	s_mov_b32 s3, 0x42b17218
	v_ldexp_f32 v2, v2, v3
	v_mul_f32_e32 v3, 0x3fb8aa3b, v1
	v_rndne_f32_e32 v4, v3
	v_sub_f32_e32 v5, v3, v4
	v_fma_f32 v3, v1, s0, -v3
	v_fmac_f32_e32 v3, 0x32a5705f, v1
	v_add_f32_e32 v3, v5, v3
	v_exp_f32_e32 v3, v3
	v_cvt_i32_f32_e32 v4, v4
	v_cndmask_b32_e32 v2, 0, v2, vcc
	v_mov_b32_e32 v5, 0x7f800000
	v_cmp_nlt_f32_e32 vcc, s3, v0
	s_add_u32 s22, s76, 0x14000000
	v_mov_b32_e32 v167, 0
	v_cndmask_b32_e32 v0, v5, v2, vcc
	v_ldexp_f32 v2, v3, v4
	v_cmp_ngt_f32_e32 vcc, s1, v1
	v_lshlrev_b32_e32 v3, 4, v160
	v_and_b32_e32 v3, 0xc0, v3
	v_cndmask_b32_e32 v2, 0, v2, vcc
	v_cmp_nlt_f32_e32 vcc, s3, v1
	v_lshlrev_b32_e32 v4, 1, v160
	v_and_b32_e32 v4, 32, v4
	v_cndmask_b32_e32 v1, v5, v2, vcc
	v_sub_f32_e32 v0, v0, v1
	v_bfe_u32 v1, v160, 5, 1
	v_lshlrev_b32_e32 v2, 3, v160
	v_and_b32_e32 v2, 24, v2
	v_lshl_or_b32 v3, v1, 8, v3
	v_or3_b32 v3, v3, v4, v2
	v_add_f32_e32 v162, 0x3e4ccccd, v0
	v_lshlrev_b32_e32 v0, 3, v1
	v_add_u32_e32 v4, 0x4100, v3
	v_lshlrev_b32_e32 v166, 4, v1
	s_addc_u32 s23, s77, 0
	v_lshl_add_u64 v[168:169], s[46:47], 0, v[166:167]
	v_lshlrev_b32_e32 v166, 1, v0
	v_add_u32_e32 v0, 0, v4
	s_add_u32 s24, s76, 0x18000000
	v_add_u32_e32 v182, 0x10400, v0
	v_mbcnt_lo_u32_b32 v0, -1, 0
	v_and_b32_e32 v161, 31, v160
	s_addc_u32 s25, s77, 0
	v_mbcnt_hi_u32_b32 v185, -1, v0
	v_and_b32_e32 v164, 63, v160
	s_add_u32 s26, s76, 0x1c000000
	v_lshlrev_b32_e32 v5, 4, v161
	s_movk_i32 s0, 0x410
	v_add_u32_e32 v179, 0, v3
	v_and_b32_e32 v0, 64, v185
	s_mov_b32 s5, 0
	s_addc_u32 s27, s77, 0
	v_bfe_u32 v165, v160, 2, 4
	v_mad_u32_u24 v178, v1, s0, v5
	v_add_u32_e32 v180, 0xc300, v179
	v_lshl_add_u32 v181, v164, 2, 0
	v_mov_b32_e32 v163, v162
	v_lshlrev_b32_e32 v170, 1, v2
	v_mov_b32_e32 v171, v167
	s_mov_b64 s[28:29], 0x80
	s_mov_b32 s3, 0x53800000
	s_mov_b64 s[30:31], 0x34000400
	v_mov_b32_e32 v183, 0x3727c5ac
	s_mov_b32 s33, 0xf800000
	v_mov_b32_e32 v184, 0x260
	s_mov_b32 s34, 0x3f4ccccd
	s_brev_b32 s35, 44
	v_xor_b32_e32 v186, 32, v185
	v_add_u32_e32 v187, 64, v0
	v_bfrev_b32_e32 v188, 1
	s_mov_b32 s36, s78
	s_branch .LBB0_294
